# v39: v37 + the 16 arrival-counter loads of the first grid barrier issued together instead of one round trip each
# baseline (speedup 1.0000x reference)
; __device__ __forceinline__ unsigned xb_ld(unsigned* p)              { return __hip_atomic_load(p, __ATOMIC_RELAXED, __HIP_MEMORY_SCOPE_AGENT); }
; __device__ __forceinline__ void xcd_barrier_complete(unsigned* bar, unsigned x, unsigned& nloc, unsigned& nx) {
;     const unsigned G = gridDim.x * gridDim.y * gridDim.z;
;     unsigned sum, cnt, mine, sp = 0u;
;     for (;;) {
;         sum = 0u; cnt = 0u; mine = 0u;
; #pragma unroll
;         for (unsigned j = 0; j < 16; ++j) { const unsigned c = xb_ld(&bar[XB_XCNT(j)]); sum += c; cnt += (c > 0u) ? 1u : 0u; mine = (j == x) ? c : mine; }
;         if (sum == G) break;
;         __builtin_amdgcn_s_sleep(1);
;         if ((++sp & 255u) == 0u) { if (xb_ld(&bar[XB_TMO])) break; if (sp > XB_SPIN_CAP) { atomicAdd(&bar[XB_TMO], 1u); break; } }
;     }
.LBB0_374:
	v_mov_b64_e32 v[18:19], s[58:59]
	flat_load_dword v1, v[18:19] offset:1024 sc1
	flat_load_dword v0, v[18:19] offset:1280 sc1
	flat_load_dword v2, v[18:19] offset:1536 sc1
	flat_load_dword v3, v[18:19] offset:1792 sc1
	flat_load_dword v4, v[18:19] offset:2048 sc1
	flat_load_dword v5, v[18:19] offset:2304 sc1
	flat_load_dword v6, v[18:19] offset:2560 sc1
	flat_load_dword v7, v[18:19] offset:2816 sc1
	flat_load_dword v8, v[18:19] offset:3072 sc1
	flat_load_dword v9, v[18:19] offset:3328 sc1
	flat_load_dword v10, v[18:19] offset:3584 sc1
	flat_load_dword v11, v[18:19] offset:3840 sc1
	v_mov_b64_e32 v[20:21], s[62:63]
	flat_load_dword v12, v[20:21] sc1
	v_mov_b64_e32 v[22:23], s[64:65]
	flat_load_dword v13, v[22:23] sc1
	v_mov_b64_e32 v[24:25], s[66:67]
	flat_load_dword v14, v[24:25] sc1
	v_mov_b64_e32 v[26:27], s[68:69]
	flat_load_dword v15, v[26:27] sc1
	s_or_b64 s[12:13], s[12:13], exec
	s_or_b64 s[10:11], s[10:11], exec
	s_waitcnt vmcnt(0) lgkmcnt(0)
	v_add_u32_e32 v16, v0, v1
	v_add3_u32 v16, v16, v2, v3
	v_add3_u32 v16, v16, v4, v5
	v_add3_u32 v16, v16, v6, v7
	v_add3_u32 v16, v16, v8, v9
	v_add3_u32 v16, v16, v10, v11
	v_add3_u32 v16, v16, v12, v13
	v_add3_u32 v16, v16, v14, v15
	v_cmp_ne_u32_e32 vcc, s55, v16
	s_and_saveexec_b64 s[14:15], vcc
	s_cbranch_execz .LBB0_373
	s_and_b32 s18, s26, 0xff
	s_mov_b64 s[16:17], -1
	s_cmp_eq_u32 s18, 0
	s_mov_b64 s[20:21], -1
	s_mov_b64 s[18:19], -1
	s_sleep 1
	s_cbranch_scc1 .LBB0_377
	s_and_saveexec_b64 s[24:25], s[20:21]
	s_cbranch_execz .LBB0_372
	s_branch .LBB0_380
